# P0: block 0 skips weight transposes (shared by other 255 blocks); its scalar loads issued up front
# baseline (speedup 1.0000x reference)
.LBB0_21:
	s_cmp_eq_u32 s92, 0
	s_cselect_b64 s[0:1], -1, 0
	s_cmp_lt_u32 s70, 64
	s_cselect_b64 s[2:3], -1, 0
	s_and_b64 s[2:3], s[0:1], s[2:3]
	v_and_b32_e32 v10, 63, v24
	s_and_b64 vcc, exec, s[2:3]
	s_cbranch_vccz .LBB0_31
	v_readlane_b32 s4, v245, 32
	v_lshlrev_b32_e32 v4, 2, v10
	v_readlane_b32 s5, v245, 33
	v_readlane_b32 s6, v245, 34
	v_readlane_b32 s7, v245, 35
	v_readlane_b32 s8, v245, 36
	v_readlane_b32 s9, v245, 37
	v_readlane_b32 s10, v245, 38
	v_readlane_b32 s11, v245, 39
	global_load_dword v1, v4, s[4:5]
	global_load_dword v5, v4, s[6:7]
	s_nop 0
	global_load_dword v6, v4, s[8:9]
	s_nop 0
	global_load_dword v7, v4, s[10:11]
	v_readlane_b32 s20, v245, 28
	v_readlane_b32 s21, v245, 29
	v_readlane_b32 s22, v245, 30
	v_readlane_b32 s23, v245, 31
	v_readlane_b32 s24, v245, 14
	v_readlane_b32 s25, v245, 15
	v_readlane_b32 s26, v245, 4
	v_readlane_b32 s27, v245, 5
	s_nop 4
	global_load_dword v20, v4, s[20:21]
	global_load_dword v21, v4, s[22:23]
	global_load_dword v22, v4, s[24:25]
	global_load_dword v23, v4, s[26:27]
	v_mbcnt_lo_u32_b32 v3, -1, 0
	v_mbcnt_hi_u32_b32 v8, -1, v3
	v_and_b32_e32 v3, 64, v8
	v_xor_b32_e32 v9, 1, v8
	v_add_u32_e32 v16, 64, v3
	v_cmp_lt_i32_e32 vcc, v9, v16
	v_xor_b32_e32 v11, 2, v8
	v_xor_b32_e32 v12, 4, v8
	v_cndmask_b32_e32 v3, v8, v9, vcc
	v_lshlrev_b32_e32 v3, 2, v3
	v_cmp_lt_i32_e32 vcc, v11, v16
	v_xor_b32_e32 v13, 8, v8
	v_xor_b32_e32 v14, 16, v8
	v_xor_b32_e32 v15, 32, v8
	v_readlane_b32 s12, v245, 40
	v_readlane_b32 s13, v245, 41
	v_readlane_b32 s14, v245, 42
	v_readlane_b32 s15, v245, 43
	v_readlane_b32 s16, v245, 44
	v_readlane_b32 s17, v245, 45
	v_readlane_b32 s18, v245, 46
	v_readlane_b32 s19, v245, 47
	s_waitcnt vmcnt(6)
	v_mul_f32_e32 v9, v1, v5
	ds_bpermute_b32 v18, v3, v9
	s_waitcnt vmcnt(4)
	v_mul_f32_e32 v17, v6, v7
	ds_bpermute_b32 v17, v3, v17
	v_cndmask_b32_e32 v9, v8, v11, vcc
	v_lshlrev_b32_e32 v9, 2, v9
	s_waitcnt lgkmcnt(1)
	v_fmac_f32_e32 v18, v1, v5
	ds_bpermute_b32 v1, v9, v18
	s_waitcnt lgkmcnt(1)
	v_fmac_f32_e32 v17, v6, v7
	ds_bpermute_b32 v5, v9, v17
	v_cmp_lt_i32_e32 vcc, v12, v16
	s_waitcnt lgkmcnt(1)
	v_add_f32_e32 v1, v18, v1
	v_cndmask_b32_e32 v6, v8, v12, vcc
	v_lshlrev_b32_e32 v11, 2, v6
	s_waitcnt lgkmcnt(0)
	v_add_f32_e32 v5, v17, v5
	ds_bpermute_b32 v6, v11, v1
	ds_bpermute_b32 v12, v11, v5
	v_cmp_lt_i32_e32 vcc, v13, v16
	s_waitcnt lgkmcnt(1)
	v_add_f32_e32 v6, v1, v6
	v_cndmask_b32_e32 v7, v8, v13, vcc
	v_lshlrev_b32_e32 v7, 2, v7
	s_waitcnt lgkmcnt(0)
	v_add_f32_e32 v5, v5, v12
	ds_bpermute_b32 v12, v7, v6
	ds_bpermute_b32 v13, v7, v5
	v_cmp_lt_i32_e32 vcc, v14, v16
	s_waitcnt lgkmcnt(1)
	v_add_f32_e32 v6, v6, v12
	v_cndmask_b32_e32 v1, v8, v14, vcc
	v_lshlrev_b32_e32 v1, 2, v1
	s_waitcnt lgkmcnt(0)
	v_add_f32_e32 v5, v5, v13
	ds_bpermute_b32 v12, v1, v6
	ds_bpermute_b32 v13, v1, v5
	v_cmp_lt_i32_e32 vcc, v15, v16
	s_waitcnt lgkmcnt(1)
	v_add_f32_e32 v12, v6, v12
	v_cndmask_b32_e32 v8, v8, v15, vcc
	v_lshlrev_b32_e32 v8, 2, v8
	s_waitcnt lgkmcnt(0)
	v_add_f32_e32 v6, v5, v13
	ds_bpermute_b32 v14, v8, v12
	ds_bpermute_b32 v13, v8, v6
	v_mov_b32_e32 v5, 0
	v_cmp_eq_u32_e32 vcc, 0, v10
	s_and_saveexec_b64 s[2:3], vcc
	s_cbranch_execz .LBB0_24
	s_waitcnt lgkmcnt(1)
	v_add_f32_e32 v12, v12, v14
	s_waitcnt lgkmcnt(0)
	v_add_f32_e32 v6, v6, v13
	v_mul_f32_e32 v12, 0x3fb8aa3b, v12
	v_mul_f32_e32 v6, 0x3fb8aa3b, v6
	v_exp_f32_e32 v12, v12
	v_exp_f32_e32 v6, v6
	s_nop 0
	v_sub_f32_e32 v6, v12, v6
	v_add_f32_e32 v6, 0x3e4ccccd, v6
	global_store_dword v5, v6, s[86:87]
.LBB0_24:
	s_or_b64 exec, exec, s[2:3]
	v_readlane_b32 s4, v245, 16
	v_readlane_b32 s16, v245, 28
	v_readlane_b32 s17, v245, 29
	v_readlane_b32 s18, v245, 30
	v_readlane_b32 s19, v245, 31
	s_nop 2
	s_nop 0
	s_nop 0
	s_nop 0
	v_readlane_b32 s5, v245, 17
	v_readlane_b32 s6, v245, 18
	v_readlane_b32 s7, v245, 19
	v_readlane_b32 s8, v245, 20
	v_readlane_b32 s9, v245, 21
	v_readlane_b32 s10, v245, 22
	v_readlane_b32 s11, v245, 23
	v_readlane_b32 s12, v245, 24
	v_readlane_b32 s13, v245, 25
	v_readlane_b32 s14, v245, 26
	v_readlane_b32 s15, v245, 27
	s_waitcnt vmcnt(2)
	global_store_dword v4, v20, s[86:87] offset:256
	s_nop 0
	global_store_dword v4, v21, s[86:87] offset:512
	s_waitcnt lgkmcnt(0)
	v_and_b32_e32 v13, 0x7fffffff, v20
	v_and_b32_e32 v14, 0x7fffffff, v21
	ds_bpermute_b32 v13, v3, v13
	ds_bpermute_b32 v14, v3, v14
	v_max_f32_e64 v15, |v20|, |v20|
	v_max_f32_e64 v16, |v21|, |v21|
	s_waitcnt lgkmcnt(1)
	v_max_f32_e32 v13, v13, v13
	s_waitcnt lgkmcnt(0)
	v_max_f32_e32 v14, v14, v14
	v_max_f32_e32 v13, v15, v13
	v_max_f32_e32 v14, v16, v14
	ds_bpermute_b32 v15, v9, v13
	ds_bpermute_b32 v16, v9, v14
	s_waitcnt lgkmcnt(1)
	v_max_f32_e32 v15, v15, v15
	s_waitcnt lgkmcnt(0)
	v_max_f32_e32 v16, v16, v16
	v_max_f32_e32 v13, v13, v15
	v_max_f32_e32 v14, v14, v16
	ds_bpermute_b32 v15, v11, v13
	ds_bpermute_b32 v16, v11, v14
	s_waitcnt lgkmcnt(1)
	v_max_f32_e32 v15, v15, v15
	s_waitcnt lgkmcnt(0)
	v_max_f32_e32 v16, v16, v16
	v_max_f32_e32 v13, v13, v15
	v_max_f32_e32 v14, v14, v16
	ds_bpermute_b32 v15, v7, v13
	ds_bpermute_b32 v16, v7, v14
	s_waitcnt lgkmcnt(1)
	v_max_f32_e32 v15, v15, v15
	s_waitcnt lgkmcnt(0)
	v_max_f32_e32 v16, v16, v16
	v_max_f32_e32 v13, v13, v15
	v_max_f32_e32 v14, v14, v16
	ds_bpermute_b32 v15, v1, v13
	ds_bpermute_b32 v16, v1, v14
	s_waitcnt lgkmcnt(1)
	v_max_f32_e32 v15, v15, v15
	s_waitcnt lgkmcnt(0)
	v_max_f32_e32 v16, v16, v16
	v_max_f32_e32 v13, v13, v15
	v_max_f32_e32 v14, v14, v16
	ds_bpermute_b32 v15, v8, v13
	ds_bpermute_b32 v16, v8, v14
	s_waitcnt lgkmcnt(1)
	v_max_f32_e32 v6, v15, v15
	s_waitcnt lgkmcnt(0)
	v_max_f32_e32 v12, v16, v16
	v_max_f32_e32 v6, v13, v6
	v_max_f32_e32 v12, v14, v12
	v_mul_f32_e32 v6, 0x4138aa3b, v6
	v_mul_f32_e32 v6, v12, v6
	v_mul_f32_e32 v6, 0x3f828f5c, v6
	s_and_saveexec_b64 s[2:3], vcc
	s_cbranch_execz .LBB0_26
	v_mov_b32_e32 v12, 0
	global_store_dword v12, v6, s[86:87] offset:4
.LBB0_26:
	s_or_b64 exec, exec, s[2:3]
	v_readlane_b32 s4, v245, 0
	v_readlane_b32 s12, v245, 8
	v_readlane_b32 s13, v245, 9
	v_readlane_b32 s14, v245, 10
	v_readlane_b32 s15, v245, 11
	v_readlane_b32 s16, v245, 12
	v_readlane_b32 s17, v245, 13
	v_readlane_b32 s18, v245, 14
	v_readlane_b32 s19, v245, 15
	s_mov_b64 s[12:13], s[16:17]
	v_readlane_b32 s5, v245, 1
	v_readlane_b32 s6, v245, 2
	v_readlane_b32 s7, v245, 3
	v_readlane_b32 s8, v245, 4
	v_readlane_b32 s9, v245, 5
	s_mov_b64 s[14:15], s[18:19]
	v_readlane_b32 s10, v245, 6
	v_readlane_b32 s11, v245, 7
	s_mov_b64 s[4:5], s[8:9]
	s_nop 0
	s_nop 0
	s_mov_b64 s[6:7], s[10:11]
	s_waitcnt vmcnt(3)
	v_and_b32_e32 v14, 0x7fffffff, v22
	s_nop 0
	v_and_b32_e32 v15, 0x7fffffff, v23
	ds_bpermute_b32 v14, v3, v14
	ds_bpermute_b32 v3, v3, v15
	v_max_f32_e64 v12, |v22|, |v22|
	v_max_f32_e64 v13, |v23|, |v23|
	s_waitcnt lgkmcnt(1)
	v_max_f32_e32 v14, v14, v14
	s_waitcnt lgkmcnt(0)
	v_max_f32_e32 v3, v3, v3
	v_max_f32_e32 v12, v12, v14
	v_max_f32_e32 v3, v13, v3
	ds_bpermute_b32 v13, v9, v12
	ds_bpermute_b32 v9, v9, v3
	s_waitcnt lgkmcnt(1)
	v_max_f32_e32 v13, v13, v13
	s_waitcnt lgkmcnt(0)
	v_max_f32_e32 v9, v9, v9
	v_max_f32_e32 v12, v12, v13
	v_max_f32_e32 v3, v3, v9
	ds_bpermute_b32 v9, v11, v12
	ds_bpermute_b32 v11, v11, v3
	s_waitcnt lgkmcnt(1)
	v_max_f32_e32 v9, v9, v9
	s_waitcnt lgkmcnt(0)
	v_max_f32_e32 v11, v11, v11
	v_max_f32_e32 v9, v12, v9
	v_max_f32_e32 v3, v3, v11
	ds_bpermute_b32 v11, v7, v9
	ds_bpermute_b32 v7, v7, v3
	s_waitcnt lgkmcnt(1)
	v_max_f32_e32 v11, v11, v11
	s_waitcnt lgkmcnt(0)
	v_max_f32_e32 v7, v7, v7
	v_max_f32_e32 v9, v9, v11
	v_max_f32_e32 v3, v3, v7
	ds_bpermute_b32 v7, v1, v9
	ds_bpermute_b32 v1, v1, v3
	s_waitcnt lgkmcnt(1)
	v_max_f32_e32 v7, v7, v7
	s_waitcnt lgkmcnt(0)
	v_max_f32_e32 v11, v1, v1
	v_max_f32_e32 v1, v9, v7
	v_max_f32_e32 v7, v3, v11
	ds_bpermute_b32 v3, v8, v1
	ds_bpermute_b32 v8, v8, v7
	s_and_saveexec_b64 s[2:3], vcc
	s_cbranch_execz .LBB0_28
	s_waitcnt lgkmcnt(1)
	v_max_f32_e32 v3, v3, v3
	v_max_f32_e32 v1, v1, v1
	s_waitcnt lgkmcnt(0)
	v_max_f32_e32 v8, v8, v8
	v_max_f32_e32 v7, v7, v7
	v_max_f32_e32 v1, v1, v3
	v_max_f32_e32 v7, v7, v8
	v_mul_f32_e32 v1, 0x4138aa3b, v1
	v_mul_f32_e32 v1, v7, v1
	v_mov_b32_e32 v9, 0
	v_mul_f32_e32 v1, 0x3f828f5c, v1
	global_store_dword v9, v1, s[86:87] offset:8

.LBB0_43:
	s_cmpk_lt_u32 s52, 8
	s_barrier
	s_cbranch_scc1 .LBB0_72
	v_lshlrev_b32_e32 v1, 2, v24
	v_readlane_b32 s8, v245, 0
	v_and_b32_e32 v4, 0x7c, v1
	v_mov_b32_e32 v5, 0
	v_lshlrev_b32_e32 v1, 3, v10
	v_readlane_b32 s9, v245, 1
	v_readlane_b32 s10, v245, 2
	v_readlane_b32 s11, v245, 3
	v_readlane_b32 s12, v245, 4
	v_readlane_b32 s13, v245, 5
	v_readlane_b32 s14, v245, 6
	v_readlane_b32 s15, v245, 7
	v_readlane_b32 s16, v245, 8
	v_readlane_b32 s17, v245, 9
	v_readlane_b32 s18, v245, 10
	v_readlane_b32 s19, v245, 11
	v_readlane_b32 s20, v245, 12
	v_readlane_b32 s21, v245, 13
	v_readlane_b32 s22, v245, 14
	v_readlane_b32 s23, v245, 15
	v_and_b32_e32 v1, 56, v1
	v_lshl_add_u64 v[12:13], s[20:21], 0, v[4:5]
	v_readlane_b32 s2, v245, 53
	v_lshl_add_u64 v[16:17], s[10:11], 0, v[4:5]
	v_readlane_b32 s8, v245, 32
	v_lshlrev_b32_e32 v26, 1, v1
	v_mov_b32_e32 v27, v5
	v_readlane_b32 s3, v245, 54
	v_readlane_b32 s9, v245, 33
	v_readlane_b32 s10, v245, 34
	v_readlane_b32 s11, v245, 35
	v_readlane_b32 s12, v245, 36
	v_readlane_b32 s13, v245, 37
	v_readlane_b32 s14, v245, 38
	v_readlane_b32 s15, v245, 39
	v_readlane_b32 s16, v245, 40
	v_readlane_b32 s17, v245, 41
	v_readlane_b32 s18, v245, 42
	v_readlane_b32 s19, v245, 43
	v_readlane_b32 s20, v245, 44
	v_readlane_b32 s21, v245, 45
	v_readlane_b32 s22, v245, 46
	v_readlane_b32 s23, v245, 47
	s_lshl_b32 s0, s71, 14
	v_lshrrev_b32_e32 v9, 3, v10
	v_lshl_add_u64 v[14:15], s[2:3], 0, v[26:27]
	v_lshl_add_u64 v[20:21], s[18:19], 0, v[4:5]
	v_readlane_b32 s2, v245, 51
	v_readlane_b32 s8, v245, 16
	s_add_i32 s0, s0, 0
	v_lshrrev_b32_e32 v2, 5, v10
	v_mul_u32_u24_e32 v3, 0x84, v1
	v_lshlrev_b32_e32 v1, 2, v9
	v_readlane_b32 s3, v245, 52
	v_readlane_b32 s18, v245, 26
	v_readlane_b32 s19, v245, 27
	s_mov_b32 s1, 0
	v_lshl_add_u64 v[6:7], s[82:83], 0, v[4:5]
	v_add_u32_e32 v8, s0, v4
	s_movk_i32 s6, 0x84
	v_lshl_add_u64 v[10:11], s[94:95], 0, v[26:27]
	v_add3_u32 v32, s0, v3, v1
	v_or_b32_e32 v33, 8, v9
	v_or_b32_e32 v34, 16, v9
	v_or_b32_e32 v35, 24, v9
	v_lshl_add_u64 v[18:19], s[58:59], 0, v[26:27]
	v_lshl_add_u64 v[22:23], s[2:3], 0, v[26:27]
	v_lshl_add_u64 v[24:25], s[18:19], 0, v[4:5]
	v_lshl_add_u64 v[26:27], s[50:51], 0, v[26:27]
	v_mov_b32_e32 v1, v2
	s_add_i32 s7, s52, -8
	v_readlane_b32 s9, v245, 17
	v_readlane_b32 s10, v245, 18
	v_readlane_b32 s11, v245, 19
	v_readlane_b32 s12, v245, 20
	v_readlane_b32 s13, v245, 21
	v_readlane_b32 s14, v245, 22
	v_readlane_b32 s15, v245, 23
	v_readlane_b32 s16, v245, 24
	v_readlane_b32 s17, v245, 25
	v_readlane_b32 s20, v245, 28
	v_readlane_b32 s21, v245, 29
	v_readlane_b32 s22, v245, 30
	v_readlane_b32 s23, v245, 31
	s_branch .LBB0_46
.LBB0_45:
	s_addk_i32 s7, 0x7f8
	s_cmpk_lt_i32 s7, 0x1080
	s_cbranch_scc0 .LBB0_72
